# P1 peeled SP1: counted vmcnt(16) wait restores formal DMA-complete guarantee after epilogue vmcnt(0) removal
# baseline (speedup 1.0000x reference)
.LBB0_383:
	s_ashr_i32 s67, s66, 31
	s_lshl_b64 s[26:27], s[66:67], 19
	s_add_u32 s26, s40, s26
	s_addc_u32 s27, s41, s27
	s_and_b64 s[34:35], s[8:9], exec
	s_cselect_b32 s34, s27, s5
	s_cselect_b32 s35, s26, s4
	s_ashr_i32 s29, s28, 31
	s_lshl_b64 s[38:39], s[28:29], 19
	s_add_u32 s62, s10, s38
	s_addc_u32 s63, s11, s39
	s_and_b64 s[38:39], s[8:9], exec
	s_cselect_b32 s29, s63, s83
	s_cselect_b32 s38, s62, s82
	s_add_u32 s39, s82, 0x100
	s_addc_u32 s67, s83, 0
	s_mov_b32 s94, -2
	s_mov_b64 vcc, 0
	v_lshl_add_u64 v[132:133], s[4:5], 0, v[168:169]
	ds_read_b128 v[134:137], v199
	ds_read_b128 v[138:141], v200
	ds_read_b128 v[142:145], v201
	ds_read_b128 v[146:149], v202
	ds_read_b128 v[150:153], v203
	ds_read_b128 v[174:177], v204
	ds_read_b128 v[178:181], v205
	ds_read_b128 v[182:185], v206
	s_add_u32 s24, s4, vcc_lo
	s_addc_u32 s25, s5, vcc_hi
	s_add_u32 s24, s24, 0x100
	s_addc_u32 s25, s25, 0
	s_add_u32 s82, s39, vcc_lo
	s_addc_u32 s83, s67, vcc_hi
	s_cmpk_eq_i32 vcc_lo, 0x700
	s_cselect_b32 s87, s29, s83
	s_cselect_b32 s86, s38, s82
	s_cselect_b32 s83, s34, s25
	s_cselect_b32 s82, s35, s24
	v_lshl_add_u64 v[154:155], v[132:133], 0, vcc
	v_lshl_add_u64 v[250:251], v[154:155], 0, s[48:49]
	s_add_i32 m0, s79, 0x8000
	s_mov_b64 s[24:25], 0x20080
	ds_read_b128 v[218:221], v207
	ds_read_b128 v[222:225], v207 offset:2048
	ds_read_b128 v[226:229], v208
	ds_read_b128 v[230:233], v208 offset:2048
	ds_read_b128 v[234:237], v207 offset:4096
	ds_read_b128 v[238:241], v207 offset:6144
	ds_read_b128 v[242:245], v208 offset:4096
	ds_read_b128 v[246:249], v208 offset:6144
	global_load_lds_dwordx4 v[250:251], off
	v_lshl_add_u64 v[250:251], v[154:155], 0, s[24:25]
	s_add_i32 m0, s79, 0xa000
	s_mov_b64 s[24:25], 0x60080
	global_load_lds_dwordx4 v[250:251], off
	v_lshl_add_u64 v[250:251], v[154:155], 0, s[50:51]
	s_add_i32 m0, s79, 0xc000
	v_lshl_add_u64 v[154:155], v[154:155], 0, s[24:25]
	global_load_lds_dwordx4 v[250:251], off
	s_add_i32 m0, s79, 0xe000
	s_nop 0
	global_load_lds_dwordx4 v[154:155], off
	s_waitcnt vmcnt(16)
	s_waitcnt lgkmcnt(0)
	s_barrier
	s_cmp_lg_u32 s98, 0
	s_cbranch_scc1 .Lp1b_skip
	v_mbcnt_lo_u32_b32 v255, -1, 0
	v_mbcnt_hi_u32_b32 v255, -1, v255
	s_cmp_gt_i32 s96, 13
	s_cbranch_scc1 .Lp1b_gate
	s_lshl_b32 s100, s96, 10
	s_add_u32 s100, s90, s100
	s_addc_u32 s101, s91, 0
	v_lshlrev_b32_e32 v255, 4, v255
	s_branch .Lp1b_issue
